# GEMM accumulator zeroing: 127 v_mov_b32 per tile replaced by 63 v_mov_b64 + 1 v_mov_b32 (5 instances)
# speedup vs baseline: 1.0116x; 1.0116x over previous
;     __device__ bool next(int i, Unit& u) const { const int L = i * G + c; if (L >= IPB_N) return false; ip_tail_tile(IPA_N - IPA_QKV + L, u); return true; }
; template <class Epi, class Sched, bool ALIGN_EPI = false, bool SP2 = false>
; __device__ __forceinline__ void gemm_phase(PG8_LAS unsigned char* lds, const Gemm g, const Sched& S, const Epi& E) {
;     ...
;         const bool has_next = S.next(ui + 1, nxt);
;         const char* nA = has_next ? (const char*)g.A + (size_t)nxt.pm * tstep : cA; const char* nB = has_next ? (const char*)g.Bt + (size_t)nxt.pn * tstep : cB;
;         for (int t = 0; t < nt; t += 2) {
;     ...
; #pragma unroll
;         for (int a = 0; a < 2; ++a)
; #pragma unroll
;             for (int b = 0; b < 2; ++b)
; #pragma unroll
;                 for (int m = 0; m < 4; ++m)
; #pragma unroll
;                     for (int n = 0; n < 2; ++n) acc[a][b][m][n] = (f32x4){0.f, 0.f, 0.f, 0.f};
.LBB0_211:
	s_ashr_i32 s25, s24, 31
	s_lshl_b64 s[14:15], s[24:25], 19
	s_add_u32 s30, s40, s14
	s_addc_u32 s31, s41, s15
	s_and_b64 s[14:15], s[28:29], exec
	s_cselect_b32 s7, s31, s5
	s_cselect_b32 s25, s30, s4
	s_ashr_i32 s27, s26, 31
	s_lshl_b64 s[14:15], s[26:27], 19
	s_add_u32 s34, s42, s14
	s_addc_u32 s35, s43, s15
	s_and_b64 s[14:15], s[28:29], exec
	s_cselect_b32 s27, s35, s1
	s_cselect_b32 s54, s34, s0
	s_add_u32 s56, s0, 0x100
	s_addc_u32 s57, s1, 0
	s_add_u32 s0, s4, 0x40080
	v_mov_b32_e32 v0, 0
	s_addc_u32 s1, s5, 0
	s_mov_b32 s58, -2
	v_mov_b32_e32 v1, v0
	v_mov_b64_e32 v[2:3], v[0:1]
	v_mov_b64_e32 v[4:5], v[0:1]
	v_mov_b64_e32 v[6:7], v[0:1]
	v_mov_b64_e32 v[8:9], v[0:1]
	v_mov_b64_e32 v[10:11], v[0:1]
	v_mov_b64_e32 v[12:13], v[0:1]
	v_mov_b64_e32 v[14:15], v[0:1]
	v_mov_b64_e32 v[16:17], v[0:1]
	v_mov_b64_e32 v[18:19], v[0:1]
	v_mov_b64_e32 v[20:21], v[0:1]
	v_mov_b64_e32 v[22:23], v[0:1]
	v_mov_b64_e32 v[24:25], v[0:1]
	v_mov_b64_e32 v[26:27], v[0:1]
	v_mov_b64_e32 v[28:29], v[0:1]
	v_mov_b64_e32 v[30:31], v[0:1]
	v_mov_b64_e32 v[48:49], v[0:1]
	v_mov_b64_e32 v[50:51], v[0:1]
	v_mov_b64_e32 v[52:53], v[0:1]
	v_mov_b64_e32 v[54:55], v[0:1]
	v_mov_b64_e32 v[56:57], v[0:1]
	v_mov_b64_e32 v[58:59], v[0:1]
	v_mov_b64_e32 v[60:61], v[0:1]
	v_mov_b64_e32 v[62:63], v[0:1]
	v_mov_b64_e32 v[64:65], v[0:1]
	v_mov_b64_e32 v[66:67], v[0:1]
	v_mov_b64_e32 v[68:69], v[0:1]
	v_mov_b64_e32 v[70:71], v[0:1]
	v_mov_b64_e32 v[72:73], v[0:1]
	v_mov_b64_e32 v[74:75], v[0:1]
	v_mov_b64_e32 v[76:77], v[0:1]
	v_mov_b64_e32 v[78:79], v[0:1]
	v_mov_b64_e32 v[80:81], v[0:1]
	v_mov_b64_e32 v[82:83], v[0:1]
	v_mov_b64_e32 v[84:85], v[0:1]
	v_mov_b64_e32 v[86:87], v[0:1]
	v_mov_b64_e32 v[88:89], v[0:1]
	v_mov_b64_e32 v[90:91], v[0:1]
	v_mov_b64_e32 v[92:93], v[0:1]
	v_mov_b64_e32 v[94:95], v[0:1]
	v_mov_b64_e32 v[96:97], v[0:1]
	v_mov_b64_e32 v[98:99], v[0:1]
	v_mov_b64_e32 v[100:101], v[0:1]
	v_mov_b64_e32 v[102:103], v[0:1]
	v_mov_b64_e32 v[104:105], v[0:1]
	v_mov_b64_e32 v[106:107], v[0:1]
	v_mov_b64_e32 v[108:109], v[0:1]
	v_mov_b64_e32 v[110:111], v[0:1]
	v_mov_b64_e32 v[112:113], v[0:1]
	v_mov_b64_e32 v[114:115], v[0:1]
	v_mov_b64_e32 v[116:117], v[0:1]
	v_mov_b64_e32 v[118:119], v[0:1]
	v_mov_b64_e32 v[120:121], v[0:1]
	v_mov_b64_e32 v[122:123], v[0:1]
	v_mov_b64_e32 v[124:125], v[0:1]
	v_mov_b64_e32 v[126:127], v[0:1]
	v_mov_b64_e32 v[128:129], v[0:1]
	v_mov_b64_e32 v[130:131], v[0:1]
	v_mov_b64_e32 v[132:133], v[0:1]
	v_mov_b64_e32 v[134:135], v[0:1]
	v_mov_b64_e32 v[136:137], v[0:1]
	v_mov_b64_e32 v[138:139], v[0:1]
	v_mov_b64_e32 v[140:141], v[0:1]
	v_mov_b64_e32 v[142:143], v[0:1]

;     __device__ bool next(int i, Unit& u) const { const int L = i * G + c; if (L >= IPB_N) return false; ip_tail_tile(IPA_N - IPA_QKV + L, u); return true; }
; template <class Epi, class Sched, bool ALIGN_EPI = false, bool SP2 = false>
; __device__ __forceinline__ void gemm_phase(PG8_LAS unsigned char* lds, const Gemm g, const Sched& S, const Epi& E) {
;     ...
;         const bool has_next = S.next(ui + 1, nxt);
;         const char* nA = has_next ? (const char*)g.A + (size_t)nxt.pm * tstep : cA; const char* nB = has_next ? (const char*)g.Bt + (size_t)nxt.pn * tstep : cB;
;         for (int t = 0; t < nt; t += 2) {
;     ...
; #pragma unroll
;         for (int a = 0; a < 2; ++a)
; #pragma unroll
;             for (int b = 0; b < 2; ++b)
; #pragma unroll
;                 for (int m = 0; m < 4; ++m)
; #pragma unroll
;                     for (int n = 0; n < 2; ++n) acc[a][b][m][n] = (f32x4){0.f, 0.f, 0.f, 0.f};
.LBB0_315:
	s_ashr_i32 s21, s20, 31
	s_lshl_b64 s[24:25], s[20:21], 19
	s_add_u32 s24, s34, s24
	s_addc_u32 s25, s35, s25
	s_and_b64 s[28:29], s[26:27], exec
	s_cselect_b32 s21, s25, s15
	s_cselect_b32 s54, s24, s14
	s_ashr_i32 s23, s22, 31
	s_lshl_b64 s[28:29], s[22:23], 19
	s_add_u32 s28, s36, s28
	s_addc_u32 s29, s37, s29
	s_and_b64 s[30:31], s[26:27], exec
	s_cselect_b32 s23, s29, s1
	s_cselect_b32 s56, s28, s0
	s_add_u32 s57, s0, 0x100
	s_addc_u32 s58, s1, 0
	s_add_u32 s0, s14, 0x40080
	v_mov_b32_e32 v0, 0
	s_addc_u32 s1, s15, 0
	s_mov_b32 s59, -2
	v_mov_b32_e32 v1, v0
	v_mov_b64_e32 v[2:3], v[0:1]
	v_mov_b64_e32 v[4:5], v[0:1]
	v_mov_b64_e32 v[6:7], v[0:1]
	v_mov_b64_e32 v[8:9], v[0:1]
	v_mov_b64_e32 v[10:11], v[0:1]
	v_mov_b64_e32 v[12:13], v[0:1]
	v_mov_b64_e32 v[14:15], v[0:1]
	v_mov_b64_e32 v[16:17], v[0:1]
	v_mov_b64_e32 v[18:19], v[0:1]
	v_mov_b64_e32 v[20:21], v[0:1]
	v_mov_b64_e32 v[22:23], v[0:1]
	v_mov_b64_e32 v[24:25], v[0:1]
	v_mov_b64_e32 v[26:27], v[0:1]
	v_mov_b64_e32 v[28:29], v[0:1]
	v_mov_b64_e32 v[30:31], v[0:1]
	v_mov_b64_e32 v[40:41], v[0:1]
	v_mov_b64_e32 v[42:43], v[0:1]
	v_mov_b64_e32 v[44:45], v[0:1]
	v_mov_b64_e32 v[46:47], v[0:1]
	v_mov_b64_e32 v[56:57], v[0:1]
	v_mov_b64_e32 v[58:59], v[0:1]
	v_mov_b64_e32 v[60:61], v[0:1]
	v_mov_b64_e32 v[62:63], v[0:1]
	v_mov_b64_e32 v[64:65], v[0:1]
	v_mov_b64_e32 v[66:67], v[0:1]
	v_mov_b64_e32 v[68:69], v[0:1]
	v_mov_b64_e32 v[70:71], v[0:1]
	v_mov_b64_e32 v[72:73], v[0:1]
	v_mov_b64_e32 v[74:75], v[0:1]
	v_mov_b64_e32 v[76:77], v[0:1]
	v_mov_b64_e32 v[78:79], v[0:1]
	v_mov_b64_e32 v[80:81], v[0:1]
	v_mov_b64_e32 v[82:83], v[0:1]
	v_mov_b64_e32 v[84:85], v[0:1]
	v_mov_b64_e32 v[86:87], v[0:1]
	v_mov_b64_e32 v[88:89], v[0:1]
	v_mov_b64_e32 v[90:91], v[0:1]
	v_mov_b64_e32 v[92:93], v[0:1]
	v_mov_b64_e32 v[94:95], v[0:1]
	v_mov_b64_e32 v[96:97], v[0:1]
	v_mov_b64_e32 v[98:99], v[0:1]
	v_mov_b64_e32 v[100:101], v[0:1]
	v_mov_b64_e32 v[102:103], v[0:1]
	v_mov_b64_e32 v[104:105], v[0:1]
	v_mov_b64_e32 v[106:107], v[0:1]
	v_mov_b64_e32 v[108:109], v[0:1]
	v_mov_b64_e32 v[110:111], v[0:1]
	v_mov_b64_e32 v[112:113], v[0:1]
	v_mov_b64_e32 v[114:115], v[0:1]
	v_mov_b64_e32 v[116:117], v[0:1]
	v_mov_b64_e32 v[118:119], v[0:1]
	v_mov_b64_e32 v[120:121], v[0:1]
	v_mov_b64_e32 v[122:123], v[0:1]
	v_mov_b64_e32 v[124:125], v[0:1]
	v_mov_b64_e32 v[126:127], v[0:1]
	v_mov_b64_e32 v[128:129], v[0:1]
	v_mov_b64_e32 v[130:131], v[0:1]
	v_mov_b64_e32 v[132:133], v[0:1]
	v_mov_b64_e32 v[134:135], v[0:1]
	v_mov_b64_e32 v[136:137], v[0:1]
	v_mov_b64_e32 v[138:139], v[0:1]
	v_mov_b64_e32 v[140:141], v[0:1]
	v_mov_b64_e32 v[142:143], v[0:1]

;     __device__ bool next(int i, Unit& u) const { const int L = i * G + c; if (L >= IPB_N) return false; ip_tail_tile(IPA_N - IPA_QKV + L, u); return true; }
; template <class Epi, class Sched, bool ALIGN_EPI = false, bool SP2 = false>
; __device__ __forceinline__ void gemm_phase(PG8_LAS unsigned char* lds, const Gemm g, const Sched& S, const Epi& E) {
;     ...
;         const bool has_next = S.next(ui + 1, nxt);
;         const char* nA = has_next ? (const char*)g.A + (size_t)nxt.pm * tstep : cA; const char* nB = has_next ? (const char*)g.Bt + (size_t)nxt.pn * tstep : cB;
;         for (int t = 0; t < nt; t += 2) {
;     ...
; #pragma unroll
;         for (int a = 0; a < 2; ++a)
; #pragma unroll
;             for (int b = 0; b < 2; ++b)
; #pragma unroll
;                 for (int m = 0; m < 4; ++m)
; #pragma unroll
;                     for (int n = 0; n < 2; ++n) acc[a][b][m][n] = (f32x4){0.f, 0.f, 0.f, 0.f};
.LBB0_909:
	s_ashr_i32 s15, s14, 31
	s_lshl_b64 s[12:13], s[14:15], 19
	s_add_u32 s40, s0, s12
	s_addc_u32 s41, s1, s13
	s_and_b64 s[12:13], s[6:7], exec
	s_cselect_b32 s15, s41, s11
	s_cselect_b32 s57, s40, s10
	s_ashr_i32 s43, s42, 31
	s_lshl_b64 s[12:13], s[42:43], 19
	s_add_u32 s44, s18, s12
	s_addc_u32 s45, s19, s13
	s_and_b64 s[12:13], s[6:7], exec
	s_cselect_b32 s43, s45, s9
	s_cselect_b32 s58, s44, s8
	s_add_u32 s59, s8, 0x100
	s_addc_u32 s68, s9, 0
	s_add_u32 s8, s10, 0x40080
	v_mov_b32_e32 v0, 0
	s_addc_u32 s9, s11, 0
	s_mov_b32 s69, -2
	s_waitcnt lgkmcnt(0)
	v_mov_b32_e32 v1, v0
	v_mov_b64_e32 v[2:3], v[0:1]
	v_mov_b64_e32 v[4:5], v[0:1]
	v_mov_b64_e32 v[6:7], v[0:1]
	v_mov_b64_e32 v[8:9], v[0:1]
	v_mov_b64_e32 v[10:11], v[0:1]
	v_mov_b64_e32 v[12:13], v[0:1]
	v_mov_b64_e32 v[14:15], v[0:1]
	v_mov_b64_e32 v[16:17], v[0:1]
	v_mov_b64_e32 v[18:19], v[0:1]
	v_mov_b64_e32 v[20:21], v[0:1]
	v_mov_b64_e32 v[22:23], v[0:1]
	v_mov_b64_e32 v[24:25], v[0:1]
	v_mov_b64_e32 v[26:27], v[0:1]
	v_mov_b64_e32 v[28:29], v[0:1]
	v_mov_b64_e32 v[30:31], v[0:1]
	v_mov_b64_e32 v[32:33], v[0:1]
	v_mov_b64_e32 v[34:35], v[0:1]
	v_mov_b64_e32 v[36:37], v[0:1]
	v_mov_b64_e32 v[38:39], v[0:1]
	v_mov_b64_e32 v[40:41], v[0:1]
	v_mov_b64_e32 v[42:43], v[0:1]
	v_mov_b64_e32 v[44:45], v[0:1]
	v_mov_b64_e32 v[46:47], v[0:1]
	v_mov_b64_e32 v[52:53], v[0:1]
	v_mov_b64_e32 v[54:55], v[0:1]
	v_mov_b64_e32 v[60:61], v[0:1]
	v_mov_b64_e32 v[62:63], v[0:1]
	v_mov_b64_e32 v[72:73], v[0:1]
	v_mov_b64_e32 v[74:75], v[0:1]
	v_mov_b64_e32 v[76:77], v[0:1]
	v_mov_b64_e32 v[78:79], v[0:1]
	v_mov_b64_e32 v[80:81], v[0:1]
	v_mov_b64_e32 v[82:83], v[0:1]
	v_mov_b64_e32 v[84:85], v[0:1]
	v_mov_b64_e32 v[86:87], v[0:1]
	v_mov_b64_e32 v[88:89], v[0:1]
	v_mov_b64_e32 v[90:91], v[0:1]
	v_mov_b64_e32 v[92:93], v[0:1]
	v_mov_b64_e32 v[94:95], v[0:1]
	v_mov_b64_e32 v[96:97], v[0:1]
	v_mov_b64_e32 v[98:99], v[0:1]
	v_mov_b64_e32 v[100:101], v[0:1]
	v_mov_b64_e32 v[102:103], v[0:1]
	v_mov_b64_e32 v[104:105], v[0:1]
	v_mov_b64_e32 v[106:107], v[0:1]
	v_mov_b64_e32 v[108:109], v[0:1]
	v_mov_b64_e32 v[110:111], v[0:1]
	v_mov_b64_e32 v[112:113], v[0:1]
	v_mov_b64_e32 v[114:115], v[0:1]
	v_mov_b64_e32 v[116:117], v[0:1]
	v_mov_b64_e32 v[118:119], v[0:1]
	v_mov_b64_e32 v[120:121], v[0:1]
	v_mov_b64_e32 v[122:123], v[0:1]
	v_mov_b64_e32 v[124:125], v[0:1]
	v_mov_b64_e32 v[126:127], v[0:1]
	v_mov_b64_e32 v[128:129], v[0:1]
	v_mov_b64_e32 v[130:131], v[0:1]
	v_mov_b64_e32 v[132:133], v[0:1]
	v_mov_b64_e32 v[134:135], v[0:1]
	v_mov_b64_e32 v[136:137], v[0:1]
	v_mov_b64_e32 v[138:139], v[0:1]
	v_mov_b64_e32 v[140:141], v[0:1]
	v_mov_b64_e32 v[142:143], v[0:1]
	s_waitcnt vmcnt(0)

;     __device__ bool next(int i, Unit& u) const { const int L = i * G + c; if (L >= IPB_N) return false; ip_tail_tile(IPA_N - IPA_QKV + L, u); return true; }
; template <class Epi, class Sched, bool ALIGN_EPI = false, bool SP2 = false>
; __device__ __forceinline__ void gemm_phase(PG8_LAS unsigned char* lds, const Gemm g, const Sched& S, const Epi& E) {
;     ...
;         const bool has_next = S.next(ui + 1, nxt);
;         const char* nA = has_next ? (const char*)g.A + (size_t)nxt.pm * tstep : cA; const char* nB = has_next ? (const char*)g.Bt + (size_t)nxt.pn * tstep : cB;
;         for (int t = 0; t < nt; t += 2) {
;     ...
; #pragma unroll
;         for (int a = 0; a < 2; ++a)
; #pragma unroll
;             for (int b = 0; b < 2; ++b)
; #pragma unroll
;                 for (int m = 0; m < 4; ++m)
; #pragma unroll
;                     for (int n = 0; n < 2; ++n) acc[a][b][m][n] = (f32x4){0.f, 0.f, 0.f, 0.f};
.LBB0_1088:
	s_ashr_i32 s21, s20, 31
	s_lshl_b64 s[22:23], s[20:21], 19
	s_add_u32 s22, s41, s22
	s_addc_u32 s23, s42, s23
	s_and_b64 s[24:25], s[4:5], exec
	s_cselect_b32 s1, s23, s31
	s_cselect_b32 s21, s22, s30
	s_ashr_i32 s19, s18, 31
	s_lshl_b64 s[24:25], s[18:19], 19
	s_add_u32 s24, s43, s24
	s_addc_u32 s25, s44, s25
	s_and_b64 s[34:35], s[4:5], exec
	s_cselect_b32 s19, s25, s29
	s_cselect_b32 s27, s24, s28
	s_add_u32 s58, s28, 0x100
	s_addc_u32 s59, s29, 0
	s_add_u32 s28, s30, 0x40080
	v_mov_b32_e32 v4, 0
	s_addc_u32 s29, s31, 0
	s_mov_b32 s62, -2
	v_mov_b32_e32 v5, v4
	v_mov_b64_e32 v[0:1], v[4:5]
	v_mov_b64_e32 v[2:3], v[4:5]
	v_mov_b64_e32 v[6:7], v[4:5]
	v_mov_b64_e32 v[8:9], v[4:5]
	v_mov_b64_e32 v[10:11], v[4:5]
	v_mov_b64_e32 v[12:13], v[4:5]
	v_mov_b64_e32 v[14:15], v[4:5]
	v_mov_b64_e32 v[16:17], v[4:5]
	v_mov_b64_e32 v[18:19], v[4:5]
	v_mov_b64_e32 v[20:21], v[4:5]
	v_mov_b64_e32 v[22:23], v[4:5]
	v_mov_b64_e32 v[24:25], v[4:5]
	v_mov_b64_e32 v[26:27], v[4:5]
	v_mov_b64_e32 v[28:29], v[4:5]
	v_mov_b64_e32 v[30:31], v[4:5]
	v_mov_b64_e32 v[32:33], v[4:5]
	v_mov_b64_e32 v[34:35], v[4:5]
	v_mov_b64_e32 v[36:37], v[4:5]
	v_mov_b64_e32 v[38:39], v[4:5]
	v_mov_b64_e32 v[40:41], v[4:5]
	v_mov_b64_e32 v[42:43], v[4:5]
	v_mov_b64_e32 v[44:45], v[4:5]
	v_mov_b64_e32 v[46:47], v[4:5]
	v_mov_b64_e32 v[48:49], v[4:5]
	v_mov_b64_e32 v[50:51], v[4:5]
	v_mov_b64_e32 v[52:53], v[4:5]
	v_mov_b64_e32 v[54:55], v[4:5]
	v_mov_b64_e32 v[56:57], v[4:5]
	v_mov_b64_e32 v[58:59], v[4:5]
	v_mov_b64_e32 v[60:61], v[4:5]
	v_mov_b64_e32 v[62:63], v[4:5]
	v_mov_b64_e32 v[64:65], v[4:5]
	v_mov_b64_e32 v[66:67], v[4:5]
	v_mov_b64_e32 v[68:69], v[4:5]
	v_mov_b64_e32 v[70:71], v[4:5]
	v_mov_b64_e32 v[72:73], v[4:5]
	v_mov_b64_e32 v[74:75], v[4:5]
	v_mov_b64_e32 v[76:77], v[4:5]
	v_mov_b64_e32 v[78:79], v[4:5]
	v_mov_b64_e32 v[88:89], v[4:5]
	v_mov_b64_e32 v[90:91], v[4:5]
	v_mov_b64_e32 v[92:93], v[4:5]
	v_mov_b64_e32 v[94:95], v[4:5]
	v_mov_b64_e32 v[96:97], v[4:5]
	v_mov_b64_e32 v[98:99], v[4:5]
	v_mov_b64_e32 v[100:101], v[4:5]
	v_mov_b64_e32 v[102:103], v[4:5]
	v_mov_b64_e32 v[104:105], v[4:5]
	v_mov_b64_e32 v[106:107], v[4:5]
	v_mov_b64_e32 v[108:109], v[4:5]
	v_mov_b64_e32 v[110:111], v[4:5]
	v_mov_b64_e32 v[112:113], v[4:5]
	v_mov_b64_e32 v[114:115], v[4:5]
	v_mov_b64_e32 v[116:117], v[4:5]
	v_mov_b64_e32 v[118:119], v[4:5]
	v_mov_b64_e32 v[120:121], v[4:5]
	v_mov_b64_e32 v[122:123], v[4:5]
	v_mov_b64_e32 v[124:125], v[4:5]
	v_mov_b64_e32 v[126:127], v[4:5]
	v_mov_b64_e32 v[128:129], v[4:5]
	v_mov_b64_e32 v[130:131], v[4:5]
	v_mov_b64_e32 v[132:133], v[4:5]
	v_mov_b64_e32 v[134:135], v[4:5]
	s_waitcnt vmcnt(0)

; template <class Epi, class Sched, bool ALIGN_EPI = false, bool SP2 = false>
; __device__ __forceinline__ void gemm_phase(PG8_LAS unsigned char* lds, const Gemm g, const Sched& S, const Epi& E) {
;     ...
;         for (int t = 0; t < nt; t += 2) {
;             const bool last = (t == nt - 2);
;             const char* a1 = cA + (size_t)(t + 1) * kstep;
;     ...
; #pragma unroll
;         for (int a = 0; a < 2; ++a)
; #pragma unroll
;             for (int b = 0; b < 2; ++b)
; #pragma unroll
;                 for (int m = 0; m < 4; ++m)
; #pragma unroll
;                     for (int n = 0; n < 2; ++n) acc[a][b][m][n] = (f32x4){0.f, 0.f, 0.f, 0.f};
.LBB0_1177:
	s_add_u32 s58, s12, 0x100
	v_mov_b32_e32 v0, 0
	s_addc_u32 s59, s13, 0
	s_mov_b32 s62, -2
	s_waitcnt lgkmcnt(0)
	v_mov_b32_e32 v1, v0
	v_mov_b64_e32 v[2:3], v[0:1]
	v_mov_b64_e32 v[4:5], v[0:1]
	v_mov_b64_e32 v[6:7], v[0:1]
	v_mov_b64_e32 v[8:9], v[0:1]
	v_mov_b64_e32 v[10:11], v[0:1]
	v_mov_b64_e32 v[12:13], v[0:1]
	v_mov_b64_e32 v[14:15], v[0:1]
	v_mov_b64_e32 v[16:17], v[0:1]
	v_mov_b64_e32 v[18:19], v[0:1]
	v_mov_b64_e32 v[20:21], v[0:1]
	v_mov_b64_e32 v[22:23], v[0:1]
	v_mov_b64_e32 v[24:25], v[0:1]
	v_mov_b64_e32 v[26:27], v[0:1]
	v_mov_b64_e32 v[28:29], v[0:1]
	v_mov_b64_e32 v[30:31], v[0:1]
	v_mov_b64_e32 v[32:33], v[0:1]
	v_mov_b64_e32 v[34:35], v[0:1]
	v_mov_b64_e32 v[36:37], v[0:1]
	v_mov_b64_e32 v[38:39], v[0:1]
	v_mov_b64_e32 v[40:41], v[0:1]
	v_mov_b64_e32 v[42:43], v[0:1]
	v_mov_b64_e32 v[44:45], v[0:1]
	v_mov_b64_e32 v[46:47], v[0:1]
	v_mov_b64_e32 v[52:53], v[0:1]
	v_mov_b64_e32 v[54:55], v[0:1]
	v_mov_b64_e32 v[56:57], v[0:1]
	v_mov_b64_e32 v[58:59], v[0:1]
	v_mov_b64_e32 v[72:73], v[0:1]
	v_mov_b64_e32 v[74:75], v[0:1]
	v_mov_b64_e32 v[76:77], v[0:1]
	v_mov_b64_e32 v[78:79], v[0:1]
	v_mov_b64_e32 v[80:81], v[0:1]
	v_mov_b64_e32 v[82:83], v[0:1]
	v_mov_b64_e32 v[84:85], v[0:1]
	v_mov_b64_e32 v[86:87], v[0:1]
	v_mov_b64_e32 v[88:89], v[0:1]
	v_mov_b64_e32 v[90:91], v[0:1]
	v_mov_b64_e32 v[92:93], v[0:1]
	v_mov_b64_e32 v[94:95], v[0:1]
	v_mov_b64_e32 v[96:97], v[0:1]
	v_mov_b64_e32 v[98:99], v[0:1]
	v_mov_b64_e32 v[100:101], v[0:1]
	v_mov_b64_e32 v[102:103], v[0:1]
	v_mov_b64_e32 v[104:105], v[0:1]
	v_mov_b64_e32 v[106:107], v[0:1]
	v_mov_b64_e32 v[108:109], v[0:1]
	v_mov_b64_e32 v[110:111], v[0:1]
	v_mov_b64_e32 v[112:113], v[0:1]
	v_mov_b64_e32 v[114:115], v[0:1]
	v_mov_b64_e32 v[116:117], v[0:1]
	v_mov_b64_e32 v[118:119], v[0:1]
	v_mov_b64_e32 v[120:121], v[0:1]
	v_mov_b64_e32 v[122:123], v[0:1]
	v_mov_b64_e32 v[124:125], v[0:1]
	v_mov_b64_e32 v[126:127], v[0:1]
	v_mov_b64_e32 v[128:129], v[0:1]
	v_mov_b64_e32 v[130:131], v[0:1]
	v_mov_b64_e32 v[132:133], v[0:1]
	v_mov_b64_e32 v[134:135], v[0:1]
	v_mov_b64_e32 v[136:137], v[0:1]
	v_mov_b64_e32 v[138:139], v[0:1]
	v_mov_b64_e32 v[140:141], v[0:1]
	v_mov_b64_e32 v[142:143], v[0:1]
	s_waitcnt vmcnt(0)
